# grid barrier poll loops sleep longer between polls (s_sleep 6)
# baseline (speedup 1.0000x reference)
.Lxbar_poll:
	global_load_dword v5, v7, s[94:95] sc1
	s_waitcnt vmcnt(0)
	v_readfirstlane_b32 s100, v5
	s_nop 3
	s_cmp_ge_u32 s100, s5
	s_cbranch_scc1 .Lxbar_rel
	s_sleep 6
	s_add_u32 s99, s99, 1
	s_cmp_lt_u32 s99, 0x400000
	s_cbranch_scc1 .Lxbar_poll

.Lxbar_poll2:
	global_load_dword v5, v8, s[94:95] sc1
	s_waitcnt vmcnt(0)
	v_readfirstlane_b32 s100, v5
	s_nop 3
	s_cmp_ge_u32 s100, s101
	s_cbranch_scc1 .Lxbar_done
	s_sleep 6
	s_add_u32 s99, s99, 1
	s_cmp_lt_u32 s99, 0x400000
	s_cbranch_scc1 .Lxbar_poll2
